# e2pf: P5 e2_rows loop software-pipelined (next iteration's rows prefetched into v60-71, gain vectors loaded once)
# baseline (speedup 1.0000x reference)
; template <int NR> DI void e2_rows(const bf16* PS, const float* gq, const float* gkv, bf16* CQN, bf16* CKVN, int m0, int mstride, int lane) {
;     u32x2 a[NR]; unsigned bq[NR];
; #pragma unroll
;     for (int r = 0; r < NR; ++r) { const bf16* ps = PS + (size_t)(m0 + r * mstride) * 1024; a[r] = *(const u32x2*)(ps + 512 + 4 * lane); bq[r] = *(const unsigned*)(ps + 768 + 2 * lane); }
;     const f32x4 g = *(const f32x4*)(gq + 4 * lane); const float g0 = gkv[2 * lane], g1 = gkv[2 * lane + 1];
; #pragma unroll
; __global__ void __launch_bounds__(512, 2) mk_fwd(Args a) {
;     ...
;         for (int m = gw; m < M; m += 4 * NGW) e2_rows<4>(PS, (const float*)a.in[9], (const float*)a.in[11], CQN, CKVN, m, NGW, lane);
.LBB0_614:
	s_cmp_lt_i32 s66, 6
	s_cselect_b64 s[2:3], -1, 0
	s_add_u32 s33, s64, 0x2aa0000
	s_addc_u32 s96, s65, 0
	v_writelane_b32 v253, s92, 53
	s_add_u32 s4, s64, 0x15bec000
	s_addc_u32 s5, s65, 0
	v_writelane_b32 v253, s93, 54
	v_writelane_b32 v253, s4, 55
	s_nop 1
	v_writelane_b32 v253, s5, 56
	s_add_u32 s4, s64, 0x3aec000
	s_addc_u32 s5, s65, 0
	s_and_b64 s[2:3], s[2:3], s[0:1]
	v_writelane_b32 v253, s4, 57
	s_andn2_b64 vcc, exec, s[2:3]
	s_nop 0
	v_writelane_b32 v253, s5, 58
	s_cbranch_vccnz .LBB0_638
	v_writelane_b32 v253, s2, 59
	s_cmpk_gt_i32 s58, 0x7fff
	s_nop 0
	v_writelane_b32 v253, s3, 60
	s_nop 0
	v_readlane_b32 s22, v253, 47
	v_readlane_b32 s23, v253, 48
	s_cbranch_scc1 .LBB0_618
	s_waitcnt lgkmcnt(0)
	v_mov_b32_e32 v1, 0
	v_readlane_b32 s0, v253, 45
	v_lshlrev_b32_e32 v8, 3, v196
	v_mov_b32_e32 v9, v1
	v_readlane_b32 s1, v253, 46
	v_lshl_add_u64 v[6:7], s[82:83], 0, v[8:9]
	v_lshlrev_b32_e32 v0, 2, v196
	v_lshl_add_u64 v[8:9], s[0:1], 0, v[8:9]
	v_readlane_b32 s0, v253, 57
	v_readlane_b32 s1, v253, 58
	v_mov_b32_e32 v5, v1
	v_lshlrev_b32_e32 v2, 1, v196
	v_lshl_add_u64 v[10:11], s[0:1], 0, v[0:1]
	v_mbcnt_lo_u32_b32 v1, -1, 0
	v_mbcnt_hi_u32_b32 v1, -1, v1
	v_and_b32_e32 v3, 64, v1
	v_add_u32_e32 v3, 64, v3
	v_xor_b32_e32 v12, 1, v1
	v_cmp_lt_i32_e32 vcc, v12, v3
	v_lshlrev_b32_e32 v4, 4, v196
	s_brev_b32 s4, 60
	v_cndmask_b32_e32 v12, v1, v12, vcc
	v_lshlrev_b32_e32 v18, 2, v12
	v_xor_b32_e32 v12, 2, v1
	v_cmp_lt_i32_e32 vcc, v12, v3
	s_mov_b32 s0, 0x358637bd
	v_lshl_add_u64 v[4:5], s[78:79], 0, v[4:5]
	v_cndmask_b32_e32 v12, v1, v12, vcc
	v_lshlrev_b32_e32 v19, 2, v12
	v_xor_b32_e32 v12, 4, v1
	v_cmp_lt_i32_e32 vcc, v12, v3
	s_lshl_b32 s12, s70, 4
	s_mul_i32 s13, s70, 24
	v_cndmask_b32_e32 v12, v1, v12, vcc
	v_lshlrev_b32_e32 v20, 2, v12
	v_xor_b32_e32 v12, 8, v1
	v_cmp_lt_i32_e32 vcc, v12, v3
	v_lshlrev_b32_e32 v24, 1, v0
	v_lshlrev_b32_e32 v25, 1, v2
	v_cndmask_b32_e32 v12, v1, v12, vcc
	v_lshlrev_b32_e32 v21, 2, v12
	v_xor_b32_e32 v12, 16, v1
	v_cmp_lt_i32_e32 vcc, v12, v3
	s_mov_b32 s5, 0x3b800000
	s_mov_b32 s14, 0x800000
	v_cndmask_b32_e32 v12, v1, v12, vcc
	v_lshlrev_b32_e32 v22, 2, v12
	v_xor_b32_e32 v12, 32, v1
	v_cmp_lt_i32_e32 vcc, v12, v3
	s_nop 1
	v_cndmask_b32_e32 v1, v1, v12, vcc
	v_lshlrev_b32_e32 v23, 2, v1
	v_mov_b64_e32 v[12:13], s[0:1]
	s_mov_b32 s0, s58
	global_load_dwordx4 v[72:75], v[4:5], off
	global_load_dwordx2 v[76:77], v[6:7], off
	s_mov_b32 s98, s0
	s_ashr_i32 s99, s98, 31
	s_lshl_b64 s[100:101], s[98:99], 11
	s_add_u32 s100, s22, s100
	s_addc_u32 s101, s23, s101
	global_load_dwordx2 v[60:61], v24, s[100:101] offset:1024
	global_load_dword v62, v25, s[100:101] offset:1536
	s_add_i32 s98, s0, s68
	s_ashr_i32 s99, s98, 31
	s_lshl_b64 s[100:101], s[98:99], 11
	s_add_u32 s100, s22, s100
	s_addc_u32 s101, s23, s101
	global_load_dwordx2 v[64:65], v24, s[100:101] offset:1024
	global_load_dword v63, v25, s[100:101] offset:1536
	s_add_i32 s98, s12, s0
	s_ashr_i32 s99, s98, 31
	s_lshl_b64 s[100:101], s[98:99], 11
	s_add_u32 s100, s22, s100
	s_addc_u32 s101, s23, s101
	global_load_dwordx2 v[66:67], v24, s[100:101] offset:1024
	global_load_dword v68, v25, s[100:101] offset:1536
	s_add_i32 s98, s13, s0
	s_ashr_i32 s99, s98, 31
	s_lshl_b64 s[100:101], s[98:99], 11
	s_add_u32 s100, s22, s100
	s_addc_u32 s101, s23, s101
	global_load_dwordx2 v[70:71], v24, s[100:101] offset:1024
	global_load_dword v69, v25, s[100:101] offset:1536
.LBB0_617:
	s_waitcnt vmcnt(0)
	v_mov_b64_e32 v[26:27], v[60:61]
	v_mov_b32_e32 v41, v62
	v_mov_b64_e32 v[28:29], v[64:65]
	v_mov_b32_e32 v48, v63
	v_mov_b64_e32 v[30:31], v[66:67]
	v_mov_b32_e32 v58, v68
	v_mov_b64_e32 v[16:17], v[70:71]
	v_mov_b32_e32 v59, v69
	v_mov_b64_e32 v[0:1], v[72:73]
	v_mov_b64_e32 v[2:3], v[74:75]
	v_mov_b64_e32 v[14:15], v[76:77]
	s_ashr_i32 s1, s0, 31
	s_lshl_b64 s[2:3], s[0:1], 11
	s_add_u32 s2, s22, s2
	s_addc_u32 s3, s23, s3
	s_add_i32 s10, s0, s68
	s_ashr_i32 s11, s10, 31
	s_lshl_b64 s[2:3], s[10:11], 11
	s_add_u32 s2, s22, s2
	s_addc_u32 s3, s23, s3
	s_add_i32 s8, s12, s0
	s_ashr_i32 s9, s8, 31
	s_add_i32 s15, s10, s68
	s_lshl_b64 s[2:3], s[8:9], 11
	s_add_u32 s2, s22, s2
	s_addc_u32 s3, s23, s3
	s_add_i32 s6, s13, s0
	s_ashr_i32 s7, s6, 31
	s_add_i32 s15, s15, s68
	s_lshl_b64 s[16:17], s[6:7], 11
	s_add_u32 s16, s22, s16
	s_addc_u32 s17, s23, s17
	s_lshl_b64 s[18:19], s[0:1], 9
	s_lshl_b64 s[0:1], s[0:1], 8
	v_lshl_add_u64 v[34:35], v[10:11], 0, s[0:1]
	v_lshl_add_u64 v[32:33], v[8:9], 0, s[18:19]
	s_lshl_b64 s[20:21], s[10:11], 9
	v_lshl_add_u64 v[36:37], v[8:9], 0, s[20:21]
	s_add_i32 s98, s15, s68
	s_cmpk_gt_i32 s98, 0x7fff
	s_cbranch_scc1 .Le2pf_skip
	s_ashr_i32 s99, s98, 31
	s_lshl_b64 s[100:101], s[98:99], 11
	s_add_u32 s100, s22, s100
	s_addc_u32 s101, s23, s101
	global_load_dwordx2 v[60:61], v24, s[100:101] offset:1024
	global_load_dword v62, v25, s[100:101] offset:1536
	s_add_i32 s98, s98, s68
	s_ashr_i32 s99, s98, 31
	s_lshl_b64 s[100:101], s[98:99], 11
	s_add_u32 s100, s22, s100
	s_addc_u32 s101, s23, s101
	global_load_dwordx2 v[64:65], v24, s[100:101] offset:1024
	global_load_dword v63, v25, s[100:101] offset:1536
	s_add_i32 s98, s15, s68
	s_add_i32 s98, s98, s12
	s_ashr_i32 s99, s98, 31
	s_lshl_b64 s[100:101], s[98:99], 11
	s_add_u32 s100, s22, s100
	s_addc_u32 s101, s23, s101
	global_load_dwordx2 v[66:67], v24, s[100:101] offset:1024
	global_load_dword v68, v25, s[100:101] offset:1536
	s_add_i32 s98, s15, s68
	s_add_i32 s98, s98, s13
	s_ashr_i32 s99, s98, 31
	s_lshl_b64 s[100:101], s[98:99], 11
	s_add_u32 s100, s22, s100
	s_addc_u32 s101, s23, s101
	global_load_dwordx2 v[70:71], v24, s[100:101] offset:1024
	global_load_dword v69, v25, s[100:101] offset:1536
; DI unsigned pk2(float lo, float hi) { f32x2_t v = {lo, hi}; bf16x2_t b = __builtin_convertvector(v, bf16x2_t); return __builtin_bit_cast(unsigned, b); }
; DI float bflo(unsigned u) { return __uint_as_float(u << 16); }
; DI float bfhi(unsigned u) { return __uint_as_float(u & 0xffff0000u); }
; template <int NR> DI void e2_rows(const bf16* PS, const float* gq, const float* gkv, bf16* CQN, bf16* CKVN, int m0, int mstride, int lane) {
;     ...
;     for (int r = 0; r < NR; ++r) { const size_t m = (size_t)(m0 + r * mstride);
;         f32x4 v = {bflo(a[r].x), bfhi(a[r].x), bflo(a[r].y), bfhi(a[r].y)};
;         float rr = rsqrtf(wave_sum((v[0] * v[0] + v[1] * v[1]) + (v[2] * v[2] + v[3] * v[3])) * (1.f / 256.f) + EPS);
;         v = v * rr * g;
;         u32x2 w; w.x = pk2(v[0], v[1]); w.y = pk2(v[2], v[3]); *(u32x2*)(CQN + m * 256 + 4 * lane) = w;
;         const float k0 = bflo(bq[r]), k1 = bfhi(bq[r]);
;         rr = rsqrtf(wave_sum(k0 * k0 + k1 * k1) * (1.f / 128.f) + EPS);
;         *(unsigned*)(CKVN + m * 128 + 2 * lane) = pk2(k0 * rr * g0, k1 * rr * g1); }
.Le2pf_skip:
	v_lshlrev_b32_e32 v39, 16, v27
	v_lshlrev_b32_e32 v38, 16, v26
	v_and_b32_e32 v27, 0xffff0000, v27
	v_and_b32_e32 v26, 0xffff0000, v26
	v_lshlrev_b32_e32 v40, 16, v41
	v_and_b32_e32 v41, 0xffff0000, v41
	v_pk_mul_f32 v[42:43], v[26:27], v[26:27]
	v_pk_mul_f32 v[44:45], v[40:41], v[40:41]
	v_mov_b32_e32 v46, v38
	v_mov_b32_e32 v47, v26
	v_mov_b32_e32 v26, v39
	v_pk_fma_f32 v[38:39], v[38:39], v[38:39], v[42:43]
	v_mov_b32_e32 v42, v44
	v_mov_b32_e32 v43, v38
	v_mov_b32_e32 v38, v45
	v_pk_add_f32 v[38:39], v[42:43], v[38:39]
	v_lshlrev_b32_e32 v43, 16, v29
	v_lshlrev_b32_e32 v42, 16, v28
	v_and_b32_e32 v29, 0xffff0000, v29
	v_and_b32_e32 v28, 0xffff0000, v28
	v_lshlrev_b32_e32 v44, 16, v48
	v_and_b32_e32 v45, 0xffff0000, v48
	ds_bpermute_b32 v49, v18, v39
	ds_bpermute_b32 v48, v18, v38
	v_pk_mul_f32 v[50:51], v[28:29], v[28:29]
	v_pk_mul_f32 v[52:53], v[44:45], v[44:45]
	v_pk_fma_f32 v[50:51], v[42:43], v[42:43], v[50:51]
	v_mov_b32_e32 v54, v52
	v_mov_b32_e32 v55, v50
	v_mov_b32_e32 v50, v53
	v_pk_add_f32 v[50:51], v[54:55], v[50:51]
	ds_bpermute_b32 v55, v18, v51
	ds_bpermute_b32 v54, v18, v50
	s_waitcnt lgkmcnt(2)
	v_pk_add_f32 v[38:39], v[38:39], v[48:49]
	ds_bpermute_b32 v49, v19, v39
	ds_bpermute_b32 v48, v19, v38
	v_lshlrev_b32_e32 v53, 16, v31
	s_waitcnt lgkmcnt(2)
	v_pk_add_f32 v[50:51], v[50:51], v[54:55]
	ds_bpermute_b32 v55, v19, v51
	ds_bpermute_b32 v54, v19, v50
	s_waitcnt lgkmcnt(2)
	v_pk_add_f32 v[38:39], v[38:39], v[48:49]
	ds_bpermute_b32 v49, v20, v39
	ds_bpermute_b32 v48, v20, v38
	v_lshlrev_b32_e32 v52, 16, v30
	s_waitcnt lgkmcnt(2)
	v_pk_add_f32 v[50:51], v[50:51], v[54:55]
	ds_bpermute_b32 v55, v20, v51
	ds_bpermute_b32 v54, v20, v50
	s_waitcnt lgkmcnt(2)
	v_pk_add_f32 v[38:39], v[38:39], v[48:49]
	ds_bpermute_b32 v49, v21, v39
	ds_bpermute_b32 v48, v21, v38
	v_and_b32_e32 v31, 0xffff0000, v31
	s_waitcnt lgkmcnt(2)
	v_pk_add_f32 v[50:51], v[50:51], v[54:55]
	ds_bpermute_b32 v55, v21, v51
	ds_bpermute_b32 v54, v21, v50
	s_waitcnt lgkmcnt(2)
	v_pk_add_f32 v[38:39], v[38:39], v[48:49]
	ds_bpermute_b32 v49, v22, v39
	ds_bpermute_b32 v48, v22, v38
	v_and_b32_e32 v30, 0xffff0000, v30
	s_waitcnt lgkmcnt(2)
	v_pk_add_f32 v[50:51], v[50:51], v[54:55]
	ds_bpermute_b32 v55, v22, v51
	ds_bpermute_b32 v54, v22, v50
	s_waitcnt lgkmcnt(2)
	v_pk_add_f32 v[38:39], v[38:39], v[48:49]
	ds_bpermute_b32 v49, v23, v39
	ds_bpermute_b32 v48, v23, v38
	v_pk_mul_f32 v[56:57], v[30:31], v[30:31]
	s_waitcnt lgkmcnt(2)
	v_pk_add_f32 v[50:51], v[50:51], v[54:55]
	ds_bpermute_b32 v55, v23, v51
	ds_bpermute_b32 v54, v23, v50
	s_waitcnt lgkmcnt(2)
	v_pk_add_f32 v[38:39], v[38:39], v[48:49]
	v_pk_fma_f32 v[56:57], v[52:53], v[52:53], v[56:57]
	v_pk_fma_f32 v[38:39], v[38:39], s[4:5], v[12:13] op_sel_hi:[1,1,0]
	s_nop 0
	v_mul_f32_e32 v48, 0x4b800000, v39
	v_mul_f32_e32 v49, 0x4b800000, v38
	v_cmp_gt_f32_e32 vcc, s14, v39
	v_cmp_gt_f32_e64 s[0:1], s14, v38
	s_nop 0
	v_cndmask_b32_e32 v39, v39, v48, vcc
	v_cndmask_b32_e64 v38, v38, v49, s[0:1]
	v_rsq_f32_e32 v48, v39
	v_rsq_f32_e32 v49, v38
	s_waitcnt lgkmcnt(0)
	v_pk_add_f32 v[38:39], v[50:51], v[54:55]
	v_mul_f32_e32 v51, 0x45800000, v49
	v_pk_fma_f32 v[38:39], v[38:39], s[4:5], v[12:13] op_sel_hi:[1,1,0]
	s_nop 0
	v_mul_f32_e32 v50, 0x4b800000, v39
	v_cmp_gt_f32_e64 s[2:3], s14, v39
	s_nop 1
	v_cndmask_b32_e64 v39, v39, v50, s[2:3]
	v_mul_f32_e32 v50, 0x45800000, v48
	v_cndmask_b32_e32 v48, v48, v50, vcc
	v_cndmask_b32_e64 v50, v49, v51, s[0:1]
	v_pk_mul_f32 v[46:47], v[48:49], v[46:47] op_sel_hi:[0,1]
	v_pk_mul_f32 v[26:27], v[48:49], v[26:27] op_sel_hi:[0,1]
	v_pk_mul_f32 v[40:41], v[50:51], v[40:41] op_sel_hi:[0,1]
	v_pk_mul_f32 v[26:27], v[2:3], v[26:27]
	v_pk_mul_f32 v[46:47], v[0:1], v[46:47]
	v_pk_mul_f32 v[40:41], v[14:15], v[40:41]
	v_cvt_pk_bf16_f32 v46, v46, v47
	v_cvt_pk_bf16_f32 v47, v26, v27
	v_cvt_pk_bf16_f32 v26, v40, v41
	global_store_dwordx2 v[32:33], v[46:47], off
	global_store_dword v[34:35], v26, off
	v_lshlrev_b32_e32 v26, 16, v58
	v_and_b32_e32 v27, 0xffff0000, v58
	v_pk_mul_f32 v[32:33], v[26:27], v[26:27]
	v_mov_b32_e32 v35, v56
	v_mov_b32_e32 v34, v32
	v_mov_b32_e32 v56, v33
	v_pk_add_f32 v[32:33], v[34:35], v[56:57]
	ds_bpermute_b32 v35, v18, v33
	ds_bpermute_b32 v34, v18, v32
	v_rsq_f32_e32 v39, v39
	v_mov_b32_e32 v47, v28
	v_mov_b32_e32 v28, v43
	v_cmp_gt_f32_e32 vcc, s14, v38
	s_waitcnt lgkmcnt(0)
	v_pk_add_f32 v[32:33], v[32:33], v[34:35]
	ds_bpermute_b32 v35, v19, v33
	ds_bpermute_b32 v34, v19, v32
	v_mul_f32_e32 v40, 0x45800000, v39
	v_cndmask_b32_e64 v40, v39, v40, s[2:3]
	v_pk_mul_f32 v[28:29], v[40:41], v[28:29] op_sel_hi:[0,1]
	v_pk_mul_f32 v[28:29], v[2:3], v[28:29]
	s_waitcnt lgkmcnt(0)
; DI unsigned pk2(float lo, float hi) { f32x2_t v = {lo, hi}; bf16x2_t b = __builtin_convertvector(v, bf16x2_t); return __builtin_bit_cast(unsigned, b); }
; DI float bflo(unsigned u) { return __uint_as_float(u << 16); }
; DI float bfhi(unsigned u) { return __uint_as_float(u & 0xffff0000u); }
; template <int NR> DI void e2_rows(const bf16* PS, const float* gq, const float* gkv, bf16* CQN, bf16* CKVN, int m0, int mstride, int lane) {
;     ...
;     for (int r = 0; r < NR; ++r) { const size_t m = (size_t)(m0 + r * mstride);
;         f32x4 v = {bflo(a[r].x), bfhi(a[r].x), bflo(a[r].y), bfhi(a[r].y)};
;         float rr = rsqrtf(wave_sum((v[0] * v[0] + v[1] * v[1]) + (v[2] * v[2] + v[3] * v[3])) * (1.f / 256.f) + EPS);
;         v = v * rr * g;
;         u32x2 w; w.x = pk2(v[0], v[1]); w.y = pk2(v[2], v[3]); *(u32x2*)(CQN + m * 256 + 4 * lane) = w;
;         const float k0 = bflo(bq[r]), k1 = bfhi(bq[r]);
;         rr = rsqrtf(wave_sum(k0 * k0 + k1 * k1) * (1.f / 128.f) + EPS);
;         *(unsigned*)(CKVN + m * 128 + 2 * lane) = pk2(k0 * rr * g0, k1 * rr * g1); }
; __global__ void __launch_bounds__(512, 2) mk_fwd(Args a) {
;     ...
;         for (int m = gw; m < M; m += 4 * NGW) e2_rows<4>(PS, (const float*)a.in[9], (const float*)a.in[11], CQN, CKVN, m, NGW, lane);
	v_pk_add_f32 v[32:33], v[32:33], v[34:35]
	ds_bpermute_b32 v35, v20, v33
	ds_bpermute_b32 v34, v20, v32
	v_mul_f32_e32 v39, 0x4b800000, v38
	v_cndmask_b32_e32 v38, v38, v39, vcc
	v_cvt_pk_bf16_f32 v39, v28, v29
	v_mov_b32_e32 v46, v42
	s_waitcnt lgkmcnt(0)
	v_pk_add_f32 v[32:33], v[32:33], v[34:35]
	ds_bpermute_b32 v35, v21, v33
	ds_bpermute_b32 v34, v21, v32
	v_rsq_f32_e32 v42, v38
	v_pk_mul_f32 v[46:47], v[40:41], v[46:47] op_sel_hi:[0,1]
	v_pk_mul_f32 v[40:41], v[0:1], v[46:47]
	s_lshl_b64 s[0:1], s[10:11], 8
	s_waitcnt lgkmcnt(0)
	v_pk_add_f32 v[28:29], v[32:33], v[34:35]
	ds_bpermute_b32 v33, v22, v29
	ds_bpermute_b32 v32, v22, v28
	v_cvt_pk_bf16_f32 v38, v40, v41
	global_store_dwordx2 v[36:37], v[38:39], off
	v_mul_f32_e32 v36, 0x45800000, v42
	v_cndmask_b32_e32 v34, v42, v36, vcc
	s_waitcnt lgkmcnt(0)
	v_pk_add_f32 v[28:29], v[28:29], v[32:33]
	ds_bpermute_b32 v33, v23, v29
	ds_bpermute_b32 v32, v23, v28
	v_pk_mul_f32 v[34:35], v[34:35], v[44:45] op_sel_hi:[0,1]
	v_pk_mul_f32 v[34:35], v[14:15], v[34:35]
	v_and_b32_e32 v37, 0xffff0000, v59
	v_cvt_pk_bf16_f32 v36, v34, v35
	s_waitcnt lgkmcnt(0)
	v_pk_add_f32 v[28:29], v[28:29], v[32:33]
	v_lshl_add_u64 v[34:35], v[10:11], 0, s[0:1]
	v_pk_fma_f32 v[28:29], v[28:29], s[4:5], v[12:13] op_sel_hi:[1,1,0]
	v_lshlrev_b32_e32 v33, 16, v17
	v_mul_f32_e32 v32, 0x4b800000, v29
	v_cmp_gt_f32_e32 vcc, s14, v29
	v_and_b32_e32 v17, 0xffff0000, v17
	global_store_dword v[34:35], v36, off
	v_cndmask_b32_e32 v29, v29, v32, vcc
	v_lshlrev_b32_e32 v32, 16, v16
	v_and_b32_e32 v16, 0xffff0000, v16
	v_pk_mul_f32 v[34:35], v[16:17], v[16:17]
	v_lshlrev_b32_e32 v36, 16, v59
	v_pk_fma_f32 v[34:35], v[32:33], v[32:33], v[34:35]
	v_pk_mul_f32 v[38:39], v[36:37], v[36:37]
	v_mov_b32_e32 v41, v34
	v_mov_b32_e32 v40, v38
	v_mov_b32_e32 v34, v39
	v_pk_add_f32 v[34:35], v[40:41], v[34:35]
	ds_bpermute_b32 v39, v18, v35
	ds_bpermute_b32 v38, v18, v34
	v_rsq_f32_e32 v29, v29
	v_mov_b32_e32 v44, v52
	v_mov_b32_e32 v45, v30
	v_mov_b32_e32 v30, v53
	s_waitcnt lgkmcnt(0)
	v_pk_add_f32 v[34:35], v[34:35], v[38:39]
	ds_bpermute_b32 v39, v19, v35
	ds_bpermute_b32 v38, v19, v34
	v_mul_f32_e32 v42, 0x45800000, v29
	v_cndmask_b32_e32 v42, v29, v42, vcc
	v_pk_mul_f32 v[44:45], v[42:43], v[44:45] op_sel_hi:[0,1]
	v_pk_mul_f32 v[30:31], v[42:43], v[30:31] op_sel_hi:[0,1]
	s_waitcnt lgkmcnt(0)
	v_pk_add_f32 v[34:35], v[34:35], v[38:39]
	ds_bpermute_b32 v39, v20, v35
	ds_bpermute_b32 v38, v20, v34
	v_pk_mul_f32 v[30:31], v[2:3], v[30:31]
	v_pk_mul_f32 v[42:43], v[0:1], v[44:45]
	v_mul_f32_e32 v29, 0x4b800000, v28
	v_cvt_pk_bf16_f32 v42, v42, v43
	v_cvt_pk_bf16_f32 v43, v30, v31
	s_waitcnt lgkmcnt(0)
	v_pk_add_f32 v[30:31], v[34:35], v[38:39]
	ds_bpermute_b32 v35, v21, v31
	ds_bpermute_b32 v34, v21, v30
	v_cmp_gt_f32_e32 vcc, s14, v28
	s_lshl_b64 s[0:1], s[8:9], 9
	v_lshl_add_u64 v[40:41], v[8:9], 0, s[0:1]
	v_cndmask_b32_e32 v28, v28, v29, vcc
	v_rsq_f32_e32 v38, v28
	s_waitcnt lgkmcnt(0)
	v_pk_add_f32 v[28:29], v[30:31], v[34:35]
	ds_bpermute_b32 v31, v22, v29
	ds_bpermute_b32 v30, v22, v28
	v_mul_f32_e32 v34, 0x45800000, v38
	v_cndmask_b32_e32 v34, v38, v34, vcc
	v_pk_mul_f32 v[26:27], v[34:35], v[26:27] op_sel_hi:[0,1]
	v_mov_b32_e32 v35, v16
	s_waitcnt lgkmcnt(0)
	v_pk_add_f32 v[28:29], v[28:29], v[30:31]
	ds_bpermute_b32 v31, v23, v29
	ds_bpermute_b32 v30, v23, v28
	v_mov_b32_e32 v16, v33
	v_pk_mul_f32 v[26:27], v[14:15], v[26:27]
	s_lshl_b64 s[0:1], s[8:9], 8
	v_cvt_pk_bf16_f32 v34, v26, v27
	s_waitcnt lgkmcnt(0)
	v_pk_add_f32 v[28:29], v[28:29], v[30:31]
	v_lshl_add_u64 v[26:27], v[10:11], 0, s[0:1]
	v_pk_fma_f32 v[28:29], v[28:29], s[4:5], v[12:13] op_sel_hi:[1,1,0]
	global_store_dwordx2 v[40:41], v[42:43], off
	v_mul_f32_e32 v30, 0x4b800000, v29
	v_cmp_gt_f32_e32 vcc, s14, v29
	global_store_dword v[26:27], v34, off
	v_mov_b32_e32 v34, v32
	v_cndmask_b32_e32 v29, v29, v30, vcc
	v_rsq_f32_e32 v29, v29
	s_lshl_b64 s[0:1], s[6:7], 9
	v_lshl_add_u64 v[26:27], v[8:9], 0, s[0:1]
	s_lshl_b64 s[0:1], s[6:7], 8
	v_mul_f32_e32 v30, 0x45800000, v29
	v_cndmask_b32_e32 v30, v29, v30, vcc
	v_pk_mul_f32 v[16:17], v[30:31], v[16:17] op_sel_hi:[0,1]
	v_pk_mul_f32 v[2:3], v[2:3], v[16:17]
	v_mul_f32_e32 v16, 0x4b800000, v28
	v_cmp_gt_f32_e32 vcc, s14, v28
	v_pk_mul_f32 v[34:35], v[30:31], v[34:35] op_sel_hi:[0,1]
	v_pk_mul_f32 v[0:1], v[0:1], v[34:35]
	v_cndmask_b32_e32 v16, v28, v16, vcc
	v_rsq_f32_e32 v16, v16
	v_cvt_pk_bf16_f32 v0, v0, v1
	v_cvt_pk_bf16_f32 v1, v2, v3
	global_store_dwordx2 v[26:27], v[0:1], off
	v_mul_f32_e32 v0, 0x45800000, v16
	v_cndmask_b32_e32 v0, v16, v0, vcc
	v_pk_mul_f32 v[0:1], v[0:1], v[36:37] op_sel_hi:[0,1]
	v_pk_mul_f32 v[0:1], v[14:15], v[0:1]
	s_nop 0
	v_cvt_pk_bf16_f32 v2, v0, v1
	v_lshl_add_u64 v[0:1], v[10:11], 0, s[0:1]
	s_add_i32 s0, s15, s68
	s_cmpk_gt_i32 s0, 0x7fff
	global_store_dword v[0:1], v2, off
	s_cbranch_scc0 .LBB0_617
